# v25 plus four spilled wave masks of the pass A prefix stage held as VGPR bitmasks (v_bfi instead of readlane pair + cndmask) and one branch test shortened to s_andn2
# speedup vs baseline: 1.0016x; 1.0016x over previous
.LBB0_661:
	v_writelane_b32 v233, s72, 28
	s_add_u32 s10, s86, 0x16b00000
	s_addc_u32 s11, s87, 0
	v_writelane_b32 v233, s73, 29
	v_writelane_b32 v233, s57, 30
	v_writelane_b32 v233, s71, 31
	s_add_u32 s0, s86, 0x1cd00000
	v_writelane_b32 v233, s0, 32
	s_addc_u32 s0, s87, 0
	v_writelane_b32 v233, s0, 33
	s_add_u32 s0, s84, 0x2000000
	s_addc_u32 s1, s85, 0
	s_add_u32 s50, s86, 0x1f700000
	v_writelane_b32 v233, s0, 34
	s_addc_u32 s51, s87, 0
	s_mov_b32 s73, 0x5040100
	v_writelane_b32 v233, s1, 35
	s_add_u32 s0, s86, 0x1f800000
	s_addc_u32 s1, s87, 0
	v_writelane_b32 v233, s0, 36
	s_ashr_i32 s71, s70, 31
	s_mov_b64 s[42:43], s[70:71]
	v_writelane_b32 v233, s1, 37
	s_ashr_i32 s0, s41, 31
	v_writelane_b32 v233, s0, 38
	s_lshl_b32 s0, s42, 5
	v_readlane_b32 s13, v233, 5
	s_and_b32 s15, s0, 0x60
	s_lshl_b32 s0, s13, 8
	s_add_i32 s48, 0, 0x12000
	s_ashr_i32 s14, s70, 3
	s_add_i32 s49, s48, s0
	s_cmp_lt_u32 s74, 64
	s_cselect_b64 s[24:25], -1, 0
	s_cmp_gt_u32 s74, 63
	s_cselect_b64 s[26:27], -1, 0
	s_cmpk_gt_u32 s74, 0x7f
	s_cselect_b64 s[0:1], -1, 0
	v_writelane_b32 v233, s0, 39
	s_cmpk_gt_u32 s74, 0xbf
	s_mul_i32 s4, s13, 0x480
	v_writelane_b32 v233, s1, 40
	s_cselect_b64 s[0:1], -1, 0
	v_writelane_b32 v233, s0, 41
	s_cmpk_gt_u32 s74, 0xff
	v_mov_b32_e32 v3, 0
	v_writelane_b32 v233, s1, 42
	s_cselect_b64 s[0:1], -1, 0
	v_writelane_b32 v233, s0, 43
	s_cmpk_gt_u32 s74, 0x13f
	s_waitcnt vmcnt(0)
	v_perm_b32 v88, v47, v0, s73
	v_writelane_b32 v233, s1, 44
	s_cselect_b64 s[0:1], -1, 0
	v_writelane_b32 v233, s0, 45
	s_cmpk_gt_u32 s74, 0x17f
	v_mov_b32_e32 v77, 0x260
	v_writelane_b32 v233, s1, 46
	s_cselect_b64 s[0:1], -1, 0
	v_writelane_b32 v233, s0, 47
	s_cmpk_gt_u32 s74, 0x1bf
	s_movk_i32 s76, 0x90
	v_writelane_b32 v233, s1, 48
	s_cselect_b64 s[0:1], -1, 0
	v_writelane_b32 v233, s0, 49
	s_cmpk_gt_u32 s74, 0x1ff
	v_mov_b64_e32 v[20:21], 0x1000
	v_writelane_b32 v233, s1, 50
	s_cselect_b64 s[0:1], -1, 0
	s_lshl_b32 s88, s13, 4
	v_writelane_b32 v233, s0, 51
	s_add_i32 s53, s88, 0
	s_lshr_b32 s5, s74, 7
	s_bfe_u32 s6, s74, 0x10006
	v_writelane_b32 v233, s1, 52
	s_cmpk_lt_u32 s74, 0x100
	s_mov_b32 s1, 0x9000
	s_cselect_b32 s0, 0, 0x2400
	s_cselect_b32 s7, s1, 0x1ce00
	s_movk_i32 s1, 0x4800
	s_cselect_b32 s8, s1, 0x6c00
	s_add_i32 s54, s0, 0
	s_bitcmp0_b32 s74, 7
	s_cselect_b32 s0, s1, 0x6c00
	s_add_i32 s55, s0, 0
	s_lshl_b32 s9, s6, 1
	s_cmpk_lt_u32 s74, 0x80
	s_cselect_b64 s[28:29], -1, 0
	s_cmp_eq_u32 s5, 2
	s_mov_b32 s0, 0x17200
	s_cselect_b32 s12, s0, 0x19600
	s_cmp_eq_u32 s5, 1
	s_cselect_b64 s[20:21], -1, 0
	s_and_b64 s[0:1], s[20:21], exec
	s_cselect_b32 s0, 0x14e00, s12
	s_add_i32 s56, s0, 0
	s_lshl_b32 s57, s6, 5
	s_lshl_b32 s58, s6, 6
	s_and_b32 s0, 64, s74
	s_cmp_eq_u32 s6, 0
	s_cselect_b64 s[30:31], -1, 0
	s_cmp_lg_u32 s0, 0
	s_cselect_b64 s[34:35], -1, 0
	s_or_b32 s62, s9, 1
	s_lshl_b32 s60, s62, 4
	s_lshl_b32 s61, s62, 5
	s_cmp_lg_u32 s13, 1
	s_mul_i32 s0, s13, 0x300
	s_cselect_b64 s[36:37], -1, 0
	s_add_i32 s64, s0, 0
	s_sub_i32 s63, s88, 64
	s_add_i32 s64, s64, 0x1ba00
	s_lshl_b32 s65, s13, 5
	s_cmpk_lt_u32 s74, 0xc0
	v_writelane_b32 v233, s74, 53
	s_cselect_b64 s[38:39], -1, 0
	s_add_i32 s0, s88, 16
	v_writelane_b32 v233, s0, 54
	s_lshl_b32 s0, s6, 3
	s_add_i32 s71, s0, 0
	s_lshl_b32 s0, s42, 9
	s_and_b32 s0, s0, 0x800
	v_writelane_b32 v233, s14, 56
	s_add_i32 s0, s14, s0
	v_writelane_b32 v233, s15, 57
	s_add_i32 s75, s0, s15
	s_load_dwordx2 s[40:41], s[82:83], 0x58
	s_load_dwordx4 s[12:15], s[82:83], 0x88
	s_lshl_b32 s69, s63, 1
	s_add_i32 s70, s69, 0
	s_lshl_b32 s1, s5, 6
	v_cndmask_b32_e64 v69, 0, 1, s[20:21]
	s_mul_i32 s59, s6, 0xa00
	s_mulk_i32 s62, 0x500
	s_add_i32 s66, s7, 0
	s_add_i32 s67, s8, 0
	s_and_b32 s68, s88, 48
	s_add_i32 s70, s70, 0x1ce00
	s_add_i32 s71, s71, s1
	s_add_i32 s72, s48, s65
	s_add_i32 s74, s4, 0
	s_add_i32 s77, 0, 0xfc00
	v_mov_b32_e32 v78, 0xf800000
	v_mov_b32_e32 v79, 0x4f800000
	v_mov_b32_e32 v124, v3
	v_mov_b32_e32 v125, v3
	v_mov_b32_e32 v80, 0x1e800
	v_mov_b32_e32 v81, 0x14400
	v_mov_b32_e32 v82, 0x900
	v_mov_b32_e32 v83, 0x1200
	v_mov_b32_e32 v87, 0x1b00
	s_mov_b32 s78, 0
	v_writelane_b32 v233, s42, 58
	s_mov_b32 s16, 0
	s_nop 0
	v_writelane_b32 v233, s43, 59
	v_mov_b32_e32 v213, v23
	v_ashrrev_i32_e32 v214, 3, v213
	v_add_u32_e32 v215, s33, v214
	v_mul_lo_u32 v216, v215, s76
	v_lshlrev_b32_e32 v217, 4, v213
	v_and_b32_e32 v218, 0x70, v217
	v_add3_u32 v130, 0, v216, v218
	v_and_b32_e32 v219, 0xffffff0, v213
	v_mul_lo_u32 v220, v219, s76
	v_lshlrev_b32_e32 v221, 1, v213
	v_add3_u32 v131, 0, v220, v221
	v_mov_b32_e32 v213, v23
	v_and_b32_e32 v214, 15, v213
	v_or_b32_e32 v215, s63, v214
	v_mul_lo_u32 v216, v215, s76
	v_and_b32_e32 v217, -16, v213
	v_add3_u32 v132, 0, v216, v217
	s_add_i32 s90, 0, 0x14e00
	v_ashrrev_i32_e32 v218, 3, v213
	v_add_u32_e32 v219, s33, v218
	v_mul_lo_u32 v220, v219, s76
	v_lshlrev_b32_e32 v221, 4, v213
	v_and_b32_e32 v222, 0x70, v221
	v_add3_u32 v133, s90, v220, v222
	s_add_i32 s91, 0, 0x14e00
	v_mov_b32_e32 v213, v23
	v_and_b32_e32 v214, 15, v213
	v_mul_u32_u24_e32 v215, 0x90, v214
	v_and_b32_e32 v216, -16, v213
	v_add3_u32 v134, s91, v215, v216
	s_add_i32 s92, 0, 0x1ba00
	v_ashrrev_i32_e32 v217, 4, v213
	s_movk_i32 s93, 0x300
	v_mul_lo_u32 v218, v217, s93
	v_mul_u32_u24_e32 v219, 48, v214
	v_add3_u32 v135, s92, v218, v219
	s_add_i32 s94, 0, 0x1ce00
	v_ashrrev_i32_e32 v220, 3, v213
	v_add_u32_e32 v221, s33, v220
	v_mul_lo_u32 v222, v221, s76
	v_lshlrev_b32_e32 v223, 4, v213
	v_and_b32_e32 v224, 0x70, v223
	v_add3_u32 v136, s94, v222, v224
	s_add_i32 s95, 0, 0x1ce00
	v_mov_b32_e32 v213, v23
	v_and_b32_e32 v214, 15, v213
	v_or_b32_e32 v215, s63, v214
	v_mul_lo_u32 v216, v215, s76
	v_ashrrev_i32_e32 v217, 4, v213
	v_lshlrev_b32_e32 v218, 3, v217
	v_add3_u32 v138, s95, v216, v218
	v_ashrrev_i32_e32 v219, 3, v213
	v_add_u32_e32 v220, s33, v219
	v_mul_lo_u32 v221, v220, s76
	v_lshlrev_b32_e32 v222, 4, v213
	v_and_b32_e32 v223, 0x70, v222
	v_add3_u32 v139, s48, v221, v223
	v_mov_b32_e32 v213, v23
	v_and_b32_e32 v214, 15, v213
	v_or_b32_e32 v215, s57, v214
	v_mul_u32_u24_e32 v216, 0x90, v215
	v_and_b32_e32 v217, -16, v213
	v_add3_u32 v140, s54, v216, v217
	v_or_b32_e32 v218, s60, v214
	v_mul_u32_u24_e32 v219, 0x90, v218
	v_add3_u32 v141, s54, v219, v217
	v_mul_u32_u24_e32 v220, 0x90, v214
	v_add_u32_e32 v221, 0x1200, v220
	v_add3_u32 v142, s55, v221, v217
	v_mov_b32_e32 v213, v23
	v_and_b32_e32 v214, 15, v213
	v_mul_u32_u24_e32 v215, 0x90, v214
	v_add_u32_e32 v216, 0x900, v215
	v_and_b32_e32 v217, -16, v213
	v_add3_u32 v143, s55, v216, v217
	v_or_b32_e32 v218, 16, v214
	v_mul_u32_u24_e32 v219, 0x90, v218
	v_add3_u32 v144, s55, v219, v217
	v_or_b32_e32 v220, 32, v214
	v_mul_u32_u24_e32 v221, 0x90, v220
	v_add3_u32 v145, s55, v221, v217
	v_mov_b32_e32 v213, v23
	v_and_b32_e32 v214, 15, v213
	v_or_b32_e32 v215, 48, v214
	v_mul_u32_u24_e32 v216, 0x90, v215
	v_and_b32_e32 v217, -16, v213
	v_add3_u32 v146, s55, v216, v217
	v_mul_lo_u32 v218, v213, s76
	v_add_u32_e32 v147, 0, v218
	v_lshlrev_b32_e32 v219, 2, v213
	v_add_u32_e32 v220, 0, v219
	v_add_u32_e32 v148, 0x12000, v220
	v_mov_b32_e32 v213, v23
	v_and_b32_e32 v214, 15, v213
	v_mul_u32_u24_e32 v215, 0x50, v214
	v_and_b32_e32 v216, -16, v213
	v_add3_u32 v217, 0, v215, v216
	v_add_u32_e32 v218, s59, v217
	v_add_u32_e32 v149, 0x14400, v218
	v_add_u32_e32 v150, 0x1e800, v218
	v_ashrrev_i32_e32 v219, 4, v213
	v_lshlrev_b32_e32 v220, 3, v219
	v_add_u32_e32 v221, s56, v220
	v_or_b32_e32 v222, s57, v214
	v_mul_u32_u24_e32 v223, 0x90, v222
	v_add_u32_e32 v151, v221, v223
	v_mov_b32_e32 v213, v23
	v_ashrrev_i32_e32 v214, 4, v213
	v_lshlrev_b32_e32 v215, 3, v214
	v_add_u32_e32 v216, s56, v215
	v_and_b32_e32 v217, 15, v213
	v_or_b32_e32 v218, s60, v217
	v_mul_u32_u24_e32 v219, 0x90, v218
	v_add_u32_e32 v152, v216, v219
	v_add_u32_e32 v220, s48, v215
	v_add_u32_e32 v221, s58, v220
	v_mul_u32_u24_e32 v222, 0x90, v217
	v_add_u32_e32 v223, 0x1200, v222
	v_add_u32_e32 v153, v221, v223
	v_mov_b32_e32 v213, v23
	v_ashrrev_i32_e32 v214, 4, v213
	v_lshlrev_b32_e32 v215, 3, v214
	v_add_u32_e32 v216, s48, v215
	v_add_u32_e32 v217, s58, v216
	v_and_b32_e32 v218, 15, v213
	v_mul_u32_u24_e32 v219, 0x90, v218
	v_add_u32_e32 v220, 0x900, v219
	v_add_u32_e32 v154, v217, v220
	v_mov_b32_e32 v213, v23
	v_ashrrev_i32_e32 v214, 4, v213
	v_lshlrev_b32_e32 v215, 3, v214
	v_add_u32_e32 v216, s48, v215
	v_add_u32_e32 v217, s58, v216
	v_and_b32_e32 v218, 15, v213
	v_mul_u32_u24_e32 v219, 0x90, v218
	v_add_u32_e32 v155, v217, v219
	v_mov_b32_e32 v220, s55
	v_mad_u32_u24 v221, v218, s76, v220
	v_and_b32_e32 v222, -16, v213
	v_add_u32_e32 v156, v221, v222
	v_mov_b32_e32 v213, v23
	v_lshlrev_b32_e32 v214, 2, v213
	v_add_u32_e32 v158, s49, v214
	v_mul_lo_u32 v215, v213, s76
	v_add_u32_e32 v159, s53, v215
	v_and_b32_e32 v160, -16, v213
	v_and_b32_e32 v161, 15, v213
	v_ashrrev_i32_e32 v162, 4, v213
	v_lshlrev_b32_e32 v216, 2, v162
	v_add_u32_e32 v217, 16, v216
	v_or_b32_e32 v218, s60, v161
	v_cmp_le_i32_e32 vcc, v217, v218
	s_nop 1
	v_cndmask_b32_e64 v219, 0, 1, vcc
	v_cmp_lt_i32_e32 vcc, v217, v218
	s_nop 1
	v_cndmask_b32_e64 v220, 0, 1, vcc
	v_cndmask_b32_e64 v221, v219, v220, s[20:21]
	v_and_b32_e32 v222, 1, v221
	v_cmp_eq_u32_e32 vcc, 1, v222
	s_nop 1
	v_cndmask_b32_e64 v163, 0, -1, vcc
	v_lshlrev_b32_e32 v213, 2, v162
	v_add_u32_e32 v214, 17, v213
	v_or_b32_e32 v215, s60, v161
	v_cmp_le_i32_e32 vcc, v214, v215
	s_nop 1
	v_cndmask_b32_e64 v216, 0, 1, vcc
	v_cmp_lt_i32_e32 vcc, v214, v215
	s_nop 1
	v_cndmask_b32_e64 v217, 0, 1, vcc
	v_cndmask_b32_e64 v218, v216, v217, s[20:21]
	v_and_b32_e32 v219, 1, v218
	v_cmp_eq_u32_e32 vcc, 1, v219
	s_nop 1
	v_cndmask_b32_e64 v164, 0, -1, vcc
	v_cmp_gt_i32_e32 vcc, 2, v162
	s_nop 1
	v_cndmask_b32_e64 v165, 0, -1, vcc
	v_or_b32_e32 v220, s57, v161
	v_or_b32_e32 v221, v213, v69
	v_cmp_gt_i32_e32 vcc, v220, v221
	s_nop 1
	v_cndmask_b32_e64 v166, 0, -1, vcc
	v_or_b32_e32 v213, s60, v161
	v_lshlrev_b32_e32 v214, 2, v162
	v_or_b32_e32 v215, v214, v69
	v_cmp_gt_i32_e32 vcc, v213, v215
	s_nop 1
	v_cndmask_b32_e64 v167, 0, -1, vcc
	v_add_u32_e32 v216, s57, v214
	v_cmp_le_i32_e32 vcc, v161, v216
	s_nop 1
	v_cndmask_b32_e64 v168, 0, -1, vcc
	v_or_b32_e32 v217, 16, v161
	v_cmp_le_i32_e32 vcc, v217, v216
	s_nop 1
	v_cndmask_b32_e64 v169, 0, -1, vcc
	v_or_b32_e32 v218, 32, v161
	v_cmp_le_i32_e32 vcc, v218, v216
	s_nop 1
	v_cndmask_b32_e64 v170, 0, -1, vcc
	v_add_u32_e32 v219, 13, v161
	v_cmp_lt_i32_e32 vcc, v219, v216
	s_nop 1
	v_cndmask_b32_e64 v171, 0, -1, vcc
	v_add_u32_e32 v220, 14, v161
	v_cmp_lt_i32_e32 vcc, v220, v216
	s_nop 1
	v_cndmask_b32_e64 v172, 0, -1, vcc
	v_lshlrev_b32_e32 v213, 2, v162
	v_add_u32_e32 v214, 16, v213
	v_cndmask_b32_e64 v215, 1, 0, s[20:21]
	v_or_b32_e32 v216, s57, v161
	v_add_u32_e32 v217, v215, v216
	v_cmp_lt_i32_e32 vcc, v214, v217
	s_nop 1
	v_cndmask_b32_e64 v173, 0, -1, vcc
	v_add_u32_e32 v218, 17, v213
	v_cmp_lt_i32_e32 vcc, v218, v217
	s_nop 1
	v_cndmask_b32_e64 v174, 0, -1, vcc
	v_add_u32_e32 v219, 18, v213
	v_cmp_lt_i32_e32 vcc, v219, v217
	s_nop 1
	v_cndmask_b32_e64 v175, 0, -1, vcc
	v_or_b32_e32 v220, s60, v161
	v_add_u32_e32 v221, v215, v220
	v_cmp_lt_i32_e32 vcc, v219, v221
	s_nop 1
	v_cndmask_b32_e64 v176, 0, -1, vcc
	v_lshlrev_b32_e32 v213, 2, v162
	v_add_u32_e32 v214, 19, v213
	v_cndmask_b32_e64 v215, 1, 0, s[20:21]
	v_or_b32_e32 v216, s57, v161
	v_add_u32_e32 v217, v215, v216
	v_cmp_lt_i32_e32 vcc, v214, v217
	s_nop 1
	v_cndmask_b32_e64 v177, 0, -1, vcc
	v_or_b32_e32 v218, s60, v161
	v_add_u32_e32 v219, v215, v218
	v_cmp_lt_i32_e32 vcc, v214, v219
	s_nop 1
	v_cndmask_b32_e64 v178, 0, -1, vcc
	v_add_u32_e32 v220, 29, v161
	v_add_u32_e32 v221, s57, v213
	v_cmp_lt_i32_e32 vcc, v220, v221
	s_nop 1
	v_cndmask_b32_e64 v179, 0, -1, vcc
	v_add_u32_e32 v213, 30, v161
	v_lshlrev_b32_e32 v214, 2, v162
	v_add_u32_e32 v215, s57, v214
	v_cmp_lt_i32_e32 vcc, v213, v215
	s_nop 1
	v_cndmask_b32_e64 v180, 0, -1, vcc
	v_add_u32_e32 v216, 32, v214
	v_cndmask_b32_e64 v217, 1, 0, s[20:21]
	v_or_b32_e32 v218, s57, v161
	v_add_u32_e32 v219, v217, v218
	v_cmp_lt_i32_e32 vcc, v216, v219
	s_nop 1
	v_cndmask_b32_e64 v181, 0, -1, vcc
	v_or_b32_e32 v220, s60, v161
	v_add_u32_e32 v221, v217, v220
	v_cmp_lt_i32_e32 vcc, v216, v221
	s_nop 1
	v_cndmask_b32_e64 v182, 0, -1, vcc
	v_lshlrev_b32_e32 v213, 2, v162
	v_add_u32_e32 v214, 33, v213
	v_cndmask_b32_e64 v215, 1, 0, s[20:21]
	v_or_b32_e32 v216, s57, v161
	v_add_u32_e32 v217, v215, v216
	v_cmp_lt_i32_e32 vcc, v214, v217
	s_nop 1
	v_cndmask_b32_e64 v183, 0, -1, vcc
	v_or_b32_e32 v218, s60, v161
	v_add_u32_e32 v219, v215, v218
	v_cmp_lt_i32_e32 vcc, v214, v219
	s_nop 1
	v_cndmask_b32_e64 v184, 0, -1, vcc
	v_add_u32_e32 v220, 34, v213
	v_cmp_lt_i32_e32 vcc, v220, v217
	s_nop 1
	v_cndmask_b32_e64 v185, 0, -1, vcc
	v_lshlrev_b32_e32 v213, 2, v162
	v_add_u32_e32 v214, 34, v213
	v_cndmask_b32_e64 v215, 1, 0, s[20:21]
	v_or_b32_e32 v216, s60, v161
	v_add_u32_e32 v217, v215, v216
	v_cmp_lt_i32_e32 vcc, v214, v217
	s_nop 1
	v_cndmask_b32_e64 v186, 0, -1, vcc
	v_add_u32_e32 v218, 35, v213
	v_or_b32_e32 v219, s57, v161
	v_add_u32_e32 v220, v215, v219
	v_cmp_lt_i32_e32 vcc, v218, v220
	s_nop 1
	v_cndmask_b32_e64 v187, 0, -1, vcc
	v_lshlrev_b32_e32 v213, 2, v162
	v_add_u32_e32 v214, 35, v213
	v_cndmask_b32_e64 v215, 1, 0, s[20:21]
	v_or_b32_e32 v216, s60, v161
	v_add_u32_e32 v217, v215, v216
	v_cmp_lt_i32_e32 vcc, v214, v217
	s_nop 1
	v_cndmask_b32_e64 v188, 0, -1, vcc
	v_add_u32_e32 v218, 48, v213
	v_cmp_lt_i32_e32 vcc, v218, v217
	s_nop 1
	v_cndmask_b32_e64 v189, 0, -1, vcc
	v_add_u32_e32 v219, 49, v213
	v_cmp_lt_i32_e32 vcc, v219, v217
	s_nop 1
	v_cndmask_b32_e64 v190, 0, -1, vcc
	v_add_u32_e32 v220, 50, v213
	v_cmp_lt_i32_e32 vcc, v220, v217
	s_nop 1
	v_cndmask_b32_e64 v191, 0, -1, vcc
	v_lshlrev_b32_e32 v213, 2, v162
	v_add_u32_e32 v214, 51, v213
	v_cndmask_b32_e64 v215, 1, 0, s[20:21]
	v_or_b32_e32 v216, s60, v161
	v_add_u32_e32 v217, v215, v216
	v_cmp_lt_i32_e32 vcc, v214, v217
	s_nop 1
	v_cndmask_b32_e64 v192, 0, -1, vcc
	v_add_u32_e32 v218, s57, v213
	v_cmp_lt_i32_e32 vcc, v161, v218
	s_nop 1
	v_cndmask_b32_e64 v193, 0, -1, vcc
	v_or_b32_e32 v219, 2, v218
	v_cmp_lt_i32_e32 vcc, v161, v219
	s_nop 1
	v_cndmask_b32_e64 v194, 0, -1, vcc
	v_or_b32_e32 v220, 3, v218
	v_cmp_lt_i32_e32 vcc, v161, v220
	s_nop 1
	v_cndmask_b32_e64 v195, 0, -1, vcc
	v_lshlrev_b32_e32 v213, 2, v162
	v_cndmask_b32_e64 v214, 1, 0, s[20:21]
	v_or_b32_e32 v215, s57, v161
	v_add_u32_e32 v216, v214, v215
	v_cmp_lt_i32_e32 vcc, v213, v216
	s_nop 1
	v_cndmask_b32_e64 v196, 0, -1, vcc
	v_or_b32_e32 v217, s60, v161
	v_add_u32_e32 v218, v214, v217
	v_cmp_lt_i32_e32 vcc, v213, v218
	s_nop 1
	v_cndmask_b32_e64 v197, 0, -1, vcc
	v_or_b32_e32 v219, 16, v161
	v_add_u32_e32 v220, s57, v213
	v_cmp_lt_i32_e32 vcc, v219, v220
	s_nop 1
	v_cndmask_b32_e64 v198, 0, -1, vcc
	v_lshlrev_b32_e32 v213, 2, v162
	v_or_b32_e32 v214, 2, v213
	v_cndmask_b32_e64 v215, 1, 0, s[20:21]
	v_or_b32_e32 v216, s57, v161
	v_add_u32_e32 v217, v215, v216
	v_cmp_lt_i32_e32 vcc, v214, v217
	s_nop 1
	v_cndmask_b32_e64 v199, 0, -1, vcc
	v_or_b32_e32 v218, s60, v161
	v_add_u32_e32 v219, v215, v218
	v_cmp_lt_i32_e32 vcc, v214, v219
	s_nop 1
	v_cndmask_b32_e64 v200, 0, -1, vcc
	v_or_b32_e32 v220, 32, v161
	v_add_u32_e32 v221, s57, v213
	v_cmp_lt_i32_e32 vcc, v220, v221
	s_nop 1
	v_cndmask_b32_e64 v201, 0, -1, vcc
	v_lshlrev_b32_e32 v213, 2, v162
	v_or_b32_e32 v214, 3, v213
	v_cndmask_b32_e64 v215, 1, 0, s[20:21]
	v_or_b32_e32 v216, s57, v161
	v_add_u32_e32 v217, v215, v216
	v_cmp_lt_i32_e32 vcc, v214, v217
	s_nop 1
	v_cndmask_b32_e64 v202, 0, -1, vcc
	v_or_b32_e32 v218, s60, v161
	v_add_u32_e32 v219, v215, v218
	v_cmp_lt_i32_e32 vcc, v214, v219
	s_nop 1
	v_cndmask_b32_e64 v203, 0, -1, vcc
	v_mov_b32_e32 v220, v23
	v_lshl_add_u32 v204, v220, 1, s74
	s_movk_i32 s96, 0x500
	v_mul_lo_u32 v213, v162, s96
	v_cmp_gt_i32_e32 vcc, 2, v162
	s_nop 1
	v_cndmask_b32_e32 v214, v80, v81, vcc
	v_add3_u32 v215, 0, v213, v214
	v_mov_b32_e32 v205, v215
	v_mov_b32_e32 v206, s16
	v_mov_b32_e32 v207, v23
	v_mul_u32_u24_e32 v208, 0x90, v161
	v_or_b32_e32 v209, 16, v161
	v_or_b32_e32 v210, 32, v161
	v_or_b32_e32 v211, 48, v161
	s_mov_b32 s96, 0x5040100
	s_mov_b32 s97, 0x7060302
	v_readlane_b32 s98, v233, 43
	v_readlane_b32 s99, v233, 44
	v_readlane_b32 s100, v233, 19
	v_readlane_b32 s101, v233, 20
	v_readlane_b32 s90, v233, 41
	v_readlane_b32 s91, v233, 42
	s_nop 3
	v_cndmask_b32_e64 v213, 0, -1, s[90:91]
	v_readlane_b32 s90, v233, 45
	v_readlane_b32 s91, v233, 46
	s_nop 3
	v_cndmask_b32_e64 v214, 0, -1, s[90:91]
	v_readlane_b32 s90, v233, 47
	v_readlane_b32 s91, v233, 48
	s_nop 3
	v_cndmask_b32_e64 v215, 0, -1, s[90:91]
	v_readlane_b32 s90, v233, 49
	v_readlane_b32 s91, v233, 50
	s_nop 3
	v_cndmask_b32_e64 v216, 0, -1, s[90:91]
	s_branch .LBB0_664

.LBB0_698:
	v_cndmask_b32_e64 v29, v34, 0, s[24:25]
	v_readlane_b32 s80, v233, 39
	v_add_f32_e32 v34, v35, v29
	v_readlane_b32 s81, v233, 40
	s_nop 1
	v_cndmask_b32_e64 v29, v29, v34, s[80:81]
	v_add_f32_e32 v32, v32, v29
	v_bfi_b32 v29, v213, v32, v29
	s_mov_b64 s[0:1], s[98:99]
	v_add_f32_e32 v32, v33, v29
	s_nop 1
	v_cndmask_b32_e64 v29, v29, v32, s[0:1]
	v_add_f32_e32 v30, v30, v29
	s_nop 0
	s_nop 0
	v_bfi_b32 v29, v214, v30, v29
	v_add_f32_e32 v31, v31, v29
	s_nop 1
	v_bfi_b32 v29, v215, v31, v29
	v_add_f32_e32 v18, v18, v29
	s_nop 1
	s_nop 0
	s_nop 1
	v_bfi_b32 v18, v216, v18, v29
	v_readlane_b32 s0, v233, 51
	v_add_f32_e32 v19, v19, v18
	v_readlane_b32 s1, v233, 52
	s_nop 1
	v_cndmask_b32_e64 v18, v18, v19, s[0:1]
	v_rsq_f32_e32 v19, s46
	s_nop 0
	v_min_f32_e32 v19, 0x5368d4a5, v19
	s_nop 0
	v_mul_f32_e32 v19, v112, v19
	v_add_f32_e32 v109, v109, v18
	v_mul_f32_e32 v17, v19, v17
	v_rsq_f32_e32 v29, s19
	s_nop 0
	v_min_f32_e32 v29, 0x5368d4a5, v29
	s_nop 0
	v_mul_f32_e32 v29, v111, v29
	v_mul_f32_e32 v15, v29, v15
	s_nop 0
	v_rsq_f32_e32 v30, s18
	s_nop 0
	v_min_f32_e32 v30, 0x5368d4a5, v30
	s_nop 0
	v_mul_f32_e32 v114, v110, v30
	v_mul_f32_e32 v16, v114, v16
	s_nop 0
	v_rsq_f32_e32 v30, s17
	s_nop 0
	v_min_f32_e32 v30, 0x5368d4a5, v30
	s_nop 0
	v_mul_f32_e32 v104, v104, v30
	v_mul_f32_e32 v14, v104, v14
	s_nop 0
	v_rsq_f32_e32 v30, s9
	s_nop 0
	v_min_f32_e32 v30, 0x5368d4a5, v30
	s_nop 0
	v_mul_f32_e32 v100, v100, v30
	v_mul_f32_e32 v13, v100, v13
	s_nop 0
	v_rsq_f32_e32 v30, s8
	s_nop 0
	v_min_f32_e32 v30, 0x5368d4a5, v30
	s_nop 0
	v_mul_f32_e32 v115, v99, v30
	v_lshlrev_b32_e32 v110, 16, v61
	v_mul_f32_e32 v11, v115, v11
	s_nop 0
	v_and_b32_e32 v31, 0xffff0000, v88
	v_rsq_f32_e32 v30, s7
	s_nop 0
	v_min_f32_e32 v30, 0x5368d4a5, v30
	s_nop 0
	v_mul_f32_e32 v116, v98, v30
	v_lshlrev_b32_e32 v30, 16, v88
	v_lshlrev_b32_e32 v33, 16, v54
	v_lshlrev_b32_e32 v35, 16, v52
	v_lshlrev_b32_e32 v34, 16, v45
	v_mov_b32_e32 v32, v31
	v_pk_add_f32 v[30:31], v[30:31], v[34:35] neg_lo:[0,1] neg_hi:[0,1]
	v_pk_add_f32 v[98:99], v[34:35], v[32:33] neg_lo:[0,1] neg_hi:[0,1]
	v_pk_fma_f32 v[30:31], v[24:25], v[30:31], v[34:35] op_sel_hi:[0,1,1]
	v_pk_fma_f32 v[34:35], v[98:99], v[24:25], v[32:33] op_sel_hi:[1,0,1]
	v_lshlrev_b32_e32 v99, 16, v66
	v_lshlrev_b32_e32 v98, 16, v56
	v_lshlrev_b32_e32 v111, 16, v71
	v_pk_mov_b32 v[32:33], v[32:33], v[110:111] op_sel:[1,0]
	v_mul_f32_e32 v12, v116, v12
	v_pk_add_f32 v[32:33], v[32:33], v[98:99] neg_lo:[0,1] neg_hi:[0,1]
	v_pk_fma_f32 v[32:33], v[32:33], v[24:25], v[98:99] op_sel_hi:[1,0,1]
	s_nop 0
	s_nop 1
	v_pk_add_f32 v[112:113], v[98:99], v[110:111] neg_lo:[0,1] neg_hi:[0,1]
	s_nop 0
	v_pk_fma_f32 v[98:99], v[112:113], v[24:25], v[110:111] op_sel_hi:[1,0,1]
	v_rsq_f32_e32 v110, s6
	s_nop 0
	v_min_f32_e32 v110, 0x5368d4a5, v110
	s_nop 0
	v_mul_f32_e32 v97, v97, v110
	v_mul_f32_e32 v110, 0x3fb8aa3b, v18
	v_exp_f32_e32 v111, v110
	v_mul_f32_e32 v110, 0x3fb8aa3b, v109
	v_exp_f32_e32 v112, v110
	v_exp_f32_e64 v110, -v110
	v_mul_f32_e32 v10, v97, v10
	v_mul_f32_e64 v97, v111, -v97
	v_mul_f32_e32 v96, v96, v112
	v_cvt_pk_bf16_f32 v109, v97, s0
	v_cvt_pk_bf16_f32 v96, v96, s0
	v_mul_f32_e32 v97, v10, v110
	v_mul_f32_e32 v111, v0, v110
	v_cvt_pk_bf16_f32 v113, v30, v31
	v_add_f32_e32 v31, v108, v18
	v_cvt_pk_bf16_f32 v97, v97, s0
	v_cvt_pk_bf16_f32 v111, v111, s0
	ds_write_b16 v204, v109
	ds_write_b16 v204, v96 offset:9216
	ds_write_b16 v204, v97 offset:18432
	ds_write_b16 v204, v111 offset:27648
	v_mul_f32_e32 v96, 0x3fb8aa3b, v31
	v_exp_f32_e32 v97, v96
	v_exp_f32_e64 v96, -v96
	v_mul_f32_e64 v31, v112, -v116
	v_cvt_pk_bf16_f32 v112, v34, v35
	v_add_f32_e32 v34, v107, v18
	v_mul_f32_e32 v111, v4, v96
	v_mul_f32_e32 v35, 0x3fb8aa3b, v34
	v_cvt_pk_bf16_f32 v31, v31, s0
	v_mul_f32_e32 v94, v94, v97
	v_mul_f32_e32 v108, v12, v96
	v_cvt_pk_bf16_f32 v111, v111, s0
	v_exp_f32_e32 v35, v35
	v_mul_f32_e32 v34, 0xbfb8aa3b, v34
	v_cvt_pk_bf16_f32 v94, v94, s0
	v_cvt_pk_bf16_f32 v108, v108, s0
	ds_write_b16 v204, v31 offset:144
	ds_write_b16 v204, v94 offset:9360
	ds_write_b16 v204, v108 offset:18576
	ds_write_b16 v204, v111 offset:27792
	v_exp_f32_e32 v111, v34
	v_mul_f32_e64 v34, v97, -v115
	v_cvt_pk_bf16_f32 v94, v34, s0
	v_mul_f32_e32 v34, v92, v35
	v_cvt_pk_bf16_f32 v34, v34, s0
	v_mul_f32_e32 v92, v11, v111
	v_mul_f32_e32 v97, v1, v111
	v_cvt_pk_bf16_f32 v92, v92, s0
	v_cvt_pk_bf16_f32 v97, v97, s0
	ds_write_b16 v204, v94 offset:288
	ds_write_b16 v204, v34 offset:9504
	ds_write_b16 v204, v92 offset:18720
	ds_write_b16 v204, v97 offset:27936
	v_add_f32_e32 v34, v106, v18
	v_mul_f32_e32 v92, 0x3fb8aa3b, v34
	v_exp_f32_e64 v97, -v92
	v_exp_f32_e32 v92, v92
	v_mul_f32_e64 v34, v35, -v100
	v_cvt_pk_bf16_f32 v100, v34, s0
	v_mul_f32_e32 v34, v90, v92
	v_cvt_pk_bf16_f32 v34, v34, s0
	v_mul_f32_e32 v35, v13, v97
	v_mul_f32_e32 v90, v5, v97
	v_cvt_pk_bf16_f32 v35, v35, s0
	v_cvt_pk_bf16_f32 v90, v90, s0
	ds_write_b16 v204, v100 offset:432
	ds_write_b16 v204, v34 offset:9648
	ds_write_b16 v204, v35 offset:18864
	ds_write_b16 v204, v90 offset:28080
	v_add_f32_e32 v34, v105, v18
	v_mul_f32_e32 v35, 0x3fb8aa3b, v34
	v_exp_f32_e64 v34, -v35
	v_exp_f32_e32 v35, v35
	v_mul_f32_e64 v90, v92, -v104
	v_cvt_pk_bf16_f32 v105, v32, v33
	v_add_f32_e32 v32, v103, v18
	v_cvt_pk_bf16_f32 v92, v90, s0
	v_mul_f32_e32 v90, v95, v35
	v_mul_f32_e32 v33, 0x3fb8aa3b, v32
	v_cvt_pk_bf16_f32 v90, v90, s0
	v_mul_f32_e32 v95, v14, v34
	v_mul_f32_e32 v104, v6, v34
	v_exp_f32_e32 v33, v33
	v_mul_f32_e32 v32, 0xbfb8aa3b, v32
	v_cvt_pk_bf16_f32 v95, v95, s0
	v_cvt_pk_bf16_f32 v104, v104, s0
	ds_write_b16 v204, v92 offset:576
	ds_write_b16 v204, v90 offset:9792
	ds_write_b16 v204, v95 offset:19008
	ds_write_b16 v204, v104 offset:28224
	v_exp_f32_e32 v90, v32
	v_mul_f32_e64 v32, v35, -v114
	v_mul_f32_e32 v35, v93, v33
	v_cvt_pk_bf16_f32 v32, v32, s0
	v_cvt_pk_bf16_f32 v35, v35, s0
	v_mul_f32_e32 v93, v16, v90
	v_mul_f32_e32 v95, v8, v90
	v_cvt_pk_bf16_f32 v93, v93, s0
	v_cvt_pk_bf16_f32 v95, v95, s0
	ds_write_b16 v204, v32 offset:720
	ds_write_b16 v204, v35 offset:9936
	ds_write_b16 v204, v93 offset:19152
	ds_write_b16 v204, v95 offset:28368
	v_add_f32_e32 v35, v102, v18
	v_mul_f32_e32 v93, 0x3fb8aa3b, v35
	v_exp_f32_e64 v35, -v93
	v_exp_f32_e32 v93, v93
	v_mul_f32_e64 v29, v33, -v29
	v_mul_f32_e32 v33, v91, v93
	v_cvt_pk_bf16_f32 v29, v29, s0
	v_cvt_pk_bf16_f32 v33, v33, s0
	v_mul_f32_e32 v91, v15, v35
	v_mul_f32_e32 v95, v7, v35
	v_add_f32_e32 v18, v101, v18
	v_cvt_pk_bf16_f32 v91, v91, s0
	v_cvt_pk_bf16_f32 v95, v95, s0
	ds_write_b16 v204, v29 offset:864
	ds_write_b16 v204, v33 offset:10080
	ds_write_b16 v204, v91 offset:19296
	ds_write_b16 v204, v95 offset:28512
	v_mul_f32_e32 v33, 0x3fb8aa3b, v18
	v_exp_f32_e64 v91, -v33
	v_exp_f32_e32 v33, v33
	v_mul_f32_e64 v18, v93, -v19
	v_mul_f32_e32 v19, v89, v33
	v_cvt_pk_bf16_f32 v18, v18, s0
	v_cvt_pk_bf16_f32 v19, v19, s0
	v_mul_f32_e32 v33, v17, v91
	v_mul_f32_e32 v89, v9, v91
	v_cvt_pk_bf16_f32 v33, v33, s0
	v_cvt_pk_bf16_f32 v89, v89, s0
	ds_write_b16 v204, v18 offset:1008
	ds_write_b16 v204, v19 offset:10224
	ds_write_b16 v204, v33 offset:19440
	ds_write_b16 v204, v89 offset:28656
	v_perm_b32 v30, v31, v109, s96
	v_perm_b32 v31, v100, v94, s96
	v_perm_b32 v33, v18, v29, s96
	v_perm_b32 v32, v32, v92, s96
	v_pk_mul_f32 v[18:19], v[2:3], v[110:111] op_sel_hi:[0,1]
	ds_write_b128 v159, v[30:33] offset:36864
	v_pk_mul_f32 v[30:31], v[2:3], v[96:97] op_sel_hi:[0,1]
	v_pk_mul_f32 v[10:11], v[10:11], v[18:19]
	v_pk_mul_f32 v[0:1], v[0:1], v[18:19]
	v_cvt_pk_bf16_f32 v32, v10, v11
	v_pk_mul_f32 v[10:11], v[12:13], v[30:31]
	v_cvt_pk_bf16_f32 v98, v98, v99
	v_cvt_pk_bf16_f32 v10, v10, v11
	v_perm_b32 v11, v10, v32, s97
	v_perm_b32 v10, v10, v32, s96
	v_pk_mul_f32 v[32:33], v[2:3], v[34:35] op_sel_hi:[0,1]
	v_pk_mul_f32 v[34:35], v[2:3], v[90:91] op_sel_hi:[0,1]
	v_pk_mul_f32 v[12:13], v[14:15], v[32:33]
	s_mov_b64 s[0:1], -1
	v_cvt_pk_bf16_f32 v2, v12, v13
	v_pk_mul_f32 v[12:13], v[16:17], v[34:35]
	s_and_b64 vcc, exec, s[80:81]
	v_cvt_pk_bf16_f32 v12, v12, v13
	v_perm_b32 v13, v12, v2, s97
	v_perm_b32 v12, v12, v2, s96
	v_cvt_pk_bf16_f32 v2, v0, v1
	v_pk_mul_f32 v[0:1], v[4:5], v[30:31]
	ds_write_b128 v159, v[10:13] offset:46080
	v_cvt_pk_bf16_f32 v0, v0, v1
	v_perm_b32 v5, v0, v2, s97
	v_perm_b32 v4, v0, v2, s96
	v_pk_mul_f32 v[0:1], v[6:7], v[32:33]
	v_mov_b32_e32 v12, s55
	v_cvt_pk_bf16_f32 v2, v0, v1
	v_pk_mul_f32 v[0:1], v[8:9], v[34:35]
	s_nop 0
	v_cvt_pk_bf16_f32 v0, v0, v1
	v_perm_b32 v7, v0, v2, s97
	v_perm_b32 v6, v0, v2, s96
	ds_write_b128 v159, v[4:7] offset:55296
	v_perm_b32 v5, v112, v113, s97
	v_perm_b32 v4, v112, v113, s96
	v_perm_b32 v7, v98, v105, s97
	v_perm_b32 v6, v98, v105, s96
	ds_write_b128 v159, v[4:7] offset:64512
	s_waitcnt lgkmcnt(0)
	s_barrier
	s_nop 0
	v_and_b32_e32 v0, 15, v28
	v_and_b32_e32 v1, -16, v28
	v_mad_u32_u24 v12, v0, s76, v12
	v_add_u32_e32 v30, v12, v1
	ds_read_b128 v[8:11], v140
	ds_read_b128 v[4:7], v140 offset:64
	ds_read_b128 v[16:19], v156
	ds_read_b128 v[12:15], v156 offset:64
	v_ashrrev_i32_e32 v2, 4, v28
	v_lshlrev_b32_e32 v29, 2, v2
	v_lshlrev_b32_e32 v2, 3, v2
	v_or_b32_e32 v89, v29, v69
	s_cbranch_vccz .LBB0_700
	s_waitcnt lgkmcnt(1)
	v_mfma_f32_16x16x32_bf16 v[94:97], v[16:19], v[8:11], 0
	s_mov_b64 s[0:1], 0
	s_waitcnt lgkmcnt(0)
	v_mfma_f32_16x16x32_bf16 v[94:97], v[12:15], v[4:7], v[94:97]
	s_nop 7
	v_bfi_b32 v35, v196, v94, v206
	v_and_b32_e32 v90, v166, v95
	v_cvt_pk_bf16_f32 v90, v35, v90
	v_and_b32_e32 v91, v199, v96
	v_and_b32_e32 v93, v202, v97
	v_cvt_pk_bf16_f32 v91, v91, v93
	ds_write_b64 v151, v[90:91]

.LBB0_750:
	s_waitcnt lgkmcnt(0)
	s_barrier
	s_andn2_b64 s[0:1], exec, s[26:27]
	v_and_b32_e32 v0, 15, v28
	v_ashrrev_i32_e32 v1, 4, v28
	s_andn2_b64 vcc, exec, s[26:27]
	s_mov_b64 s[4:5], -1
	s_cbranch_vccnz .LBB0_764
	s_and_b64 vcc, exec, s[36:37]
	s_cbranch_vccz .LBB0_755
	s_mov_b64 s[4:5], s[98:99]
	s_andn2_b64 vcc, exec, s[4:5]
	s_cbranch_vccnz .LBB0_754
	v_and_b32_e32 v8, -16, v28
	v_mul_u32_u24_e32 v4, 0x90, v0
	s_add_i32 s4, 0, 0x14e00
	v_add3_u32 v29, s4, v4, v8
	ds_read_b128 v[4:7], v134
	v_or_b32_e32 v2, s63, v0
	v_mul_lo_u32 v2, v2, s76
	ds_read_b128 v[8:11], v134 offset:64
	ds_read_b128 v[12:15], v132 offset:64512
	ds_read_b128 v[16:19], v132 offset:64576
	s_add_i32 s4, 0, 0x1ce00
	v_lshlrev_b32_e32 v30, 3, v1
	s_waitcnt lgkmcnt(1)
	v_mfma_f32_16x16x32_bf16 v[4:7], v[4:7], v[12:15], 0
	v_add3_u32 v2, s4, v2, v30
	s_waitcnt lgkmcnt(0)
	v_mfma_f32_16x16x32_bf16 v[4:7], v[8:11], v[16:19], v[4:7]
	s_nop 7
	v_cvt_pk_bf16_f32 v4, v4, v5
	v_cvt_pk_bf16_f32 v5, v6, v7
	ds_write_b64 v138, v[4:5]
	ds_read_b128 v[4:7], v134 offset:2304
	ds_read_b128 v[8:11], v134 offset:2368
	s_waitcnt lgkmcnt(1)
	v_mfma_f32_16x16x32_bf16 v[4:7], v[4:7], v[12:15], 0
	s_waitcnt lgkmcnt(0)
	v_mfma_f32_16x16x32_bf16 v[4:7], v[8:11], v[16:19], v[4:7]
	s_nop 7
	v_cvt_pk_bf16_f32 v4, v4, v5
	v_cvt_pk_bf16_f32 v5, v6, v7
	ds_write_b64 v138, v[4:5] offset:32
	ds_read_b128 v[4:7], v134 offset:4608
	ds_read_b128 v[8:11], v134 offset:4672
	s_waitcnt lgkmcnt(1)
	v_mfma_f32_16x16x32_bf16 v[4:7], v[4:7], v[12:15], 0
	s_waitcnt lgkmcnt(0)
	v_mfma_f32_16x16x32_bf16 v[4:7], v[8:11], v[16:19], v[4:7]
	s_nop 7
	v_cvt_pk_bf16_f32 v4, v4, v5
	v_cvt_pk_bf16_f32 v5, v6, v7
	ds_write_b64 v138, v[4:5] offset:64
	ds_read_b128 v[4:7], v134 offset:6912
	ds_read_b128 v[8:11], v134 offset:6976
	s_waitcnt lgkmcnt(1)
	v_mfma_f32_16x16x32_bf16 v[4:7], v[4:7], v[12:15], 0
	s_waitcnt lgkmcnt(0)
	v_mfma_f32_16x16x32_bf16 v[4:7], v[8:11], v[16:19], v[4:7]
	s_nop 7
	v_cvt_pk_bf16_f32 v4, v4, v5
	v_cvt_pk_bf16_f32 v5, v6, v7
	ds_write_b64 v138, v[4:5] offset:96
